# GEMM k-loops: next group's double-buffered reads issued two per MFMA slot in the first three slots; next iteration's scalar prelude and address VALU moved ahead of the k-tile barrier
# baseline (speedup 1.0000x reference)
; #define MFMA(a, b, c) __builtin_amdgcn_mfma_f32_32x32x16_bf16((a), (b), (c), 0, 0, 0)
;     ...
;     auto compute2 = [&](int buf) {
;       const char* lb = L0 + buf * BUFB;
; #pragma unroll
;       for (int ks = 0; ks < 4; ++ks) {
;         const int c = ks * 2 + hh;
;         bf16x8 wf[2], xf[MI];
; #pragma unroll
;         for (int j = 0; j < 2; ++j) { const int r = wn * 64 + j * 32 + l32; wf[j] = *(const bf16x8*)(lb + 256 * 128 + r * 128 + ((c ^ ((r >> 1) & 7)) << 4)); }
; #pragma unroll
;         for (int i = 0; i < MI; ++i) { const int r = wm * (MI * 32) + i * 32 + l32; xf[i] = *(const bf16x8*)(lb + r * 128 + ((c ^ ((r >> 1) & 7)) << 4)); }
; #pragma unroll
;         for (int i = 0; i < MI; ++i) {
;           acc[i][0] = MFMA(wf[0], xf[i], acc[i][0]);
;           acc[i][1] = MFMA(wf[1], xf[i], acc[i][1]);
;         }
;       }
;     ...
;       for (int kt = 0; kt < nk; ++kt) {
;         const int buf = kt & 1;
;         if (kt + 1 < nk) issue(kt + 1, buf ^ 1);
;         else if (chain & 2) issue_at(nmt * 256, nnt * BN, 0, buf ^ 1);
;         compute2(buf);
;         asm volatile("s_waitcnt vmcnt(0)" ::: "memory");
;         __syncthreads();
;       }
.LBB0_798:
	v_writelane_b32 v255, s60, 0
	v_writelane_b32 v255, s61, 1
	v_writelane_b32 v255, s62, 2
	v_writelane_b32 v255, s63, 3
	v_writelane_b32 v255, s64, 4
	v_add_u32_e32 v0, v168, v169
	v_add_u32_e32 v178, v160, v169
	v_add_u32_e32 v199, v162, v169
	v_add_u32_e32 v254, v166, v169
	s_nop 0
	v_readfirstlane_b32 s60, v0
	v_readfirstlane_b32 s61, v178
	v_readfirstlane_b32 s62, v199
	v_readfirstlane_b32 s63, v254
	s_and_b32 s14, s11, 0x10000
	s_xor_b32 s15, s14, 0x10000
	s_add_i32 s15, s15, 0
	s_add_i32 s14, s14, 0
	v_add_u32_e32 v0, s14, v175
	v_add_u32_e32 v176, v0, v171
	v_add_u32_e32 v0, v0, v170
	ds_read_b128 v[200:203], v176 offset:32768
	ds_read_b128 v[204:207], v176 offset:36864
	ds_read_b128 v[208:211], v0
	ds_read_b128 v[212:215], v0 offset:4096
	ds_read_b128 v[216:219], v0 offset:8192
	ds_read_b128 v[220:223], v0 offset:12288
	s_add_i32 s64, s15, 0x8000
	s_add_i32 m0, s15, s60
	v_lshl_add_u64 v[176:177], v[152:153], 0, s[2:3]
	global_load_lds_dwordx4 v[176:177], off
	s_add_i32 m0, s15, s61
	v_lshl_add_u64 v[176:177], v[150:151], 0, s[2:3]
	global_load_lds_dwordx4 v[176:177], off
	s_add_i32 m0, s15, s62
	v_lshl_add_u64 v[176:177], v[148:149], 0, s[2:3]
	global_load_lds_dwordx4 v[176:177], off
	s_add_i32 m0, s15, s63
	v_lshl_add_u64 v[176:177], v[146:147], 0, s[2:3]
	global_load_lds_dwordx4 v[176:177], off
	s_add_i32 m0, s64, s60
	v_lshl_add_u64 v[176:177], v[144:145], 0, s[2:3]
	global_load_lds_dwordx4 v[176:177], off
	s_add_i32 m0, s64, s61
	v_lshl_add_u64 v[176:177], v[142:143], 0, s[2:3]
	global_load_lds_dwordx4 v[176:177], off
	s_add_i32 m0, s64, s62
	v_lshl_add_u64 v[176:177], v[140:141], 0, s[2:3]
	global_load_lds_dwordx4 v[176:177], off
	s_add_i32 m0, s64, s63
	v_lshl_add_u64 v[176:177], v[138:139], 0, s[2:3]
	global_load_lds_dwordx4 v[176:177], off
	v_add_u32_e32 v0, s14, v174
	v_add_u32_e32 v176, v0, v171
	v_add_u32_e32 v0, v0, v170
	s_waitcnt lgkmcnt(3)
	v_mfma_f32_32x32x16_bf16 v[114:129], v[200:203], v[208:211], 0
	s_add_i32 s11, s11, 0x10000
	s_add_u32 s2, s2, 0x80
	s_addc_u32 s3, s3, 0
	s_cmpk_eq_i32 s2, 0x780
	ds_read_b128 v[224:227], v176 offset:32768
	ds_read_b128 v[228:231], v176 offset:36864
	v_mfma_f32_32x32x16_bf16 v[98:113], v[204:207], v[208:211], 0
	ds_read_b128 v[232:235], v0
	ds_read_b128 v[240:243], v0 offset:4096
	s_waitcnt lgkmcnt(6)
	v_mfma_f32_32x32x16_bf16 v[82:97], v[200:203], v[212:215], 0
	ds_read_b128 v[244:247], v0 offset:8192
	ds_read_b128 v[248:251], v0 offset:12288
	v_mfma_f32_32x32x16_bf16 v[66:81], v[204:207], v[212:215], 0
	s_waitcnt lgkmcnt(7)
	v_mfma_f32_32x32x16_bf16 v[50:65], v[200:203], v[216:219], 0
	v_mfma_f32_32x32x16_bf16 v[34:49], v[204:207], v[216:219], 0
	s_waitcnt lgkmcnt(6)
	v_mfma_f32_32x32x16_bf16 v[18:33], v[200:203], v[220:223], 0
	v_mfma_f32_32x32x16_bf16 v[2:17], v[204:207], v[220:223], 0
	s_branch .Lgemm_g1_798
.Lgemm_rot_798:
	v_add_u32_e32 v0, s14, v174
	v_add_u32_e32 v176, v0, v171
	v_add_u32_e32 v0, v0, v170
	s_waitcnt lgkmcnt(3)
	v_mfma_f32_32x32x16_bf16 v[114:129], v[200:203], v[208:211], v[114:129]
	s_add_i32 s11, s11, 0x10000
	s_add_u32 s2, s2, 0x80
	s_addc_u32 s3, s3, 0
	s_cmpk_eq_i32 s2, 0x780
	ds_read_b128 v[224:227], v176 offset:32768
	ds_read_b128 v[228:231], v176 offset:36864
	v_mfma_f32_32x32x16_bf16 v[98:113], v[204:207], v[208:211], v[98:113]
	ds_read_b128 v[232:235], v0
	ds_read_b128 v[240:243], v0 offset:4096
	s_waitcnt lgkmcnt(6)
	v_mfma_f32_32x32x16_bf16 v[82:97], v[200:203], v[212:215], v[82:97]
	ds_read_b128 v[244:247], v0 offset:8192
	ds_read_b128 v[248:251], v0 offset:12288
	v_mfma_f32_32x32x16_bf16 v[66:81], v[204:207], v[212:215], v[66:81]
	s_waitcnt lgkmcnt(7)
	v_mfma_f32_32x32x16_bf16 v[50:65], v[200:203], v[216:219], v[50:65]
	v_mfma_f32_32x32x16_bf16 v[34:49], v[204:207], v[216:219], v[34:49]
	s_waitcnt lgkmcnt(6)
	v_mfma_f32_32x32x16_bf16 v[18:33], v[200:203], v[220:223], v[18:33]
	v_mfma_f32_32x32x16_bf16 v[2:17], v[204:207], v[220:223], v[2:17]
.Lgemm_g1_798:
	v_add_u32_e32 v0, s14, v173
	v_add_u32_e32 v176, v0, v171
	v_add_u32_e32 v0, v0, v170
	s_waitcnt lgkmcnt(3)
	v_mfma_f32_32x32x16_bf16 v[114:129], v[224:227], v[232:235], v[114:129]
	ds_read_b128 v[200:203], v176 offset:32768
	ds_read_b128 v[204:207], v176 offset:36864
	v_mfma_f32_32x32x16_bf16 v[98:113], v[228:231], v[232:235], v[98:113]
	ds_read_b128 v[208:211], v0
	ds_read_b128 v[212:215], v0 offset:4096
	s_waitcnt lgkmcnt(6)
	v_mfma_f32_32x32x16_bf16 v[82:97], v[224:227], v[240:243], v[82:97]
	ds_read_b128 v[216:219], v0 offset:8192
	ds_read_b128 v[220:223], v0 offset:12288
	v_mfma_f32_32x32x16_bf16 v[66:81], v[228:231], v[240:243], v[66:81]
	s_waitcnt lgkmcnt(7)
	v_mfma_f32_32x32x16_bf16 v[50:65], v[224:227], v[244:247], v[50:65]
	v_mfma_f32_32x32x16_bf16 v[34:49], v[228:231], v[244:247], v[34:49]
	s_waitcnt lgkmcnt(6)
	v_mfma_f32_32x32x16_bf16 v[18:33], v[224:227], v[248:251], v[18:33]
	v_mfma_f32_32x32x16_bf16 v[2:17], v[228:231], v[248:251], v[2:17]
	v_add_u32_e32 v0, s14, v172
	v_add_u32_e32 v176, v0, v171
	v_add_u32_e32 v0, v0, v170
	s_waitcnt lgkmcnt(3)
	v_mfma_f32_32x32x16_bf16 v[114:129], v[200:203], v[208:211], v[114:129]
	ds_read_b128 v[224:227], v176 offset:32768
	ds_read_b128 v[228:231], v176 offset:36864
	v_mfma_f32_32x32x16_bf16 v[98:113], v[204:207], v[208:211], v[98:113]
	ds_read_b128 v[232:235], v0
	ds_read_b128 v[240:243], v0 offset:4096
	s_waitcnt lgkmcnt(6)
	v_mfma_f32_32x32x16_bf16 v[82:97], v[200:203], v[212:215], v[82:97]
	ds_read_b128 v[244:247], v0 offset:8192
	ds_read_b128 v[248:251], v0 offset:12288
	v_mfma_f32_32x32x16_bf16 v[66:81], v[204:207], v[212:215], v[66:81]
	s_waitcnt lgkmcnt(7)
	v_mfma_f32_32x32x16_bf16 v[50:65], v[200:203], v[216:219], v[50:65]
	v_mfma_f32_32x32x16_bf16 v[34:49], v[204:207], v[216:219], v[34:49]
	s_waitcnt lgkmcnt(6)
	v_mfma_f32_32x32x16_bf16 v[18:33], v[200:203], v[220:223], v[18:33]
	v_mfma_f32_32x32x16_bf16 v[2:17], v[204:207], v[220:223], v[2:17]
	s_waitcnt vmcnt(0)
	s_waitcnt vmcnt(0) lgkmcnt(0)
	s_cbranch_scc1 .Lgemm_exit_798
;     ...
;       for (int kt = 0; kt < nk; ++kt) {
;         const int buf = kt & 1;
;         if (kt + 1 < nk) issue(kt + 1, buf ^ 1);
;         else if (chain & 2) issue_at(nmt * 256, nnt * BN, 0, buf ^ 1);
;         compute2(buf);
;         asm volatile("s_waitcnt vmcnt(0)" ::: "memory");
;         __syncthreads();
;       }
; template <int MODE, int EPI, int BN>
; DI void gemm_phase(CP p, const GArgs& g, int NT, char* smem) {
;     ...
;   for (int e = j; e < total; e += nj) {
;     const int grp = e / (8 * NT);
;     const int rem = e - grp * 8 * NT;
;     const int e2 = e + nj;
;     const bool has_next = can_chain && e2 < total;
;     const int grp2 = e2 / (8 * NT), rem2 = e2 - grp2 * 8 * NT;
;     const int chain = can_chain ? ((first ? 0 : 1) | (has_next ? 2 : 0)) : 0;
;     gemm_tile<MODE, EPI, BN>(p, g, x + 8 * (grp * 8 + (rem & 7)), rem >> 3, smem, chain, x + 8 * (grp2 * 8 + (rem2 & 7)), rem2 >> 3);
	s_and_b32 s14, s11, 0x10000
	s_xor_b32 s15, s14, 0x10000
	s_add_i32 s15, s15, 0
	s_add_i32 s14, s14, 0
	v_add_u32_e32 v0, s14, v175
	v_add_u32_e32 v176, v0, v171
	v_add_u32_e32 v0, v0, v170
	s_barrier
	ds_read_b128 v[200:203], v176 offset:32768
	ds_read_b128 v[204:207], v176 offset:36864
	ds_read_b128 v[208:211], v0
	ds_read_b128 v[212:215], v0 offset:4096
	ds_read_b128 v[216:219], v0 offset:8192
	ds_read_b128 v[220:223], v0 offset:12288
	v_mfma_f32_32x32x16_bf16 v[114:129], v[224:227], v[232:235], v[114:129]
	s_add_i32 s64, s15, 0x8000
	s_add_i32 m0, s15, s60
	v_lshl_add_u64 v[176:177], v[152:153], 0, s[2:3]
	global_load_lds_dwordx4 v[176:177], off
	v_mfma_f32_32x32x16_bf16 v[98:113], v[228:231], v[232:235], v[98:113]
	s_add_i32 m0, s15, s61
	v_lshl_add_u64 v[176:177], v[150:151], 0, s[2:3]
	global_load_lds_dwordx4 v[176:177], off
	s_add_i32 m0, s15, s62
	v_mfma_f32_32x32x16_bf16 v[82:97], v[224:227], v[240:243], v[82:97]
	v_lshl_add_u64 v[176:177], v[148:149], 0, s[2:3]
	global_load_lds_dwordx4 v[176:177], off
	s_add_i32 m0, s15, s63
	v_lshl_add_u64 v[176:177], v[146:147], 0, s[2:3]
	v_mfma_f32_32x32x16_bf16 v[66:81], v[228:231], v[240:243], v[66:81]
	global_load_lds_dwordx4 v[176:177], off
	s_add_i32 m0, s64, s60
	v_lshl_add_u64 v[176:177], v[144:145], 0, s[2:3]
	global_load_lds_dwordx4 v[176:177], off
	v_mfma_f32_32x32x16_bf16 v[50:65], v[224:227], v[244:247], v[50:65]
	s_add_i32 m0, s64, s61
	v_lshl_add_u64 v[176:177], v[142:143], 0, s[2:3]
	global_load_lds_dwordx4 v[176:177], off
	s_add_i32 m0, s64, s62
	v_mfma_f32_32x32x16_bf16 v[34:49], v[228:231], v[244:247], v[34:49]
	v_lshl_add_u64 v[176:177], v[140:141], 0, s[2:3]
	global_load_lds_dwordx4 v[176:177], off
	s_add_i32 m0, s64, s63
	v_lshl_add_u64 v[176:177], v[138:139], 0, s[2:3]
	v_mfma_f32_32x32x16_bf16 v[18:33], v[224:227], v[248:251], v[18:33]
	global_load_lds_dwordx4 v[176:177], off
	v_mfma_f32_32x32x16_bf16 v[2:17], v[228:231], v[248:251], v[2:17]
	s_branch .Lgemm_rot_798
.Lgemm_exit_798:
	s_barrier
	v_readlane_b32 s60, v255, 0
	v_readlane_b32 s61, v255, 1
	v_readlane_b32 s62, v255, 2
	v_readlane_b32 s63, v255, 3
	v_readlane_b32 s64, v255, 4
	v_mfma_f32_32x32x16_bf16 v[114:129], v[224:227], v[232:235], v[114:129]
	v_mfma_f32_32x32x16_bf16 v[98:113], v[228:231], v[232:235], v[98:113]
	v_mfma_f32_32x32x16_bf16 v[82:97], v[224:227], v[240:243], v[82:97]
	v_mfma_f32_32x32x16_bf16 v[66:81], v[228:231], v[240:243], v[66:81]
	v_mfma_f32_32x32x16_bf16 v[50:65], v[224:227], v[244:247], v[50:65]
	v_mfma_f32_32x32x16_bf16 v[34:49], v[228:231], v[244:247], v[34:49]
	v_mfma_f32_32x32x16_bf16 v[18:33], v[224:227], v[248:251], v[18:33]
	v_mfma_f32_32x32x16_bf16 v[2:17], v[228:231], v[248:251], v[2:17]
	s_add_i32 s95, s95, s76
	s_cmpk_gt_u32 s95, 0x9f
	s_cselect_b64 s[92:93], -1, 0
	s_and_b64 vcc, exec, s[92:93]
	s_cbranch_vccnz .LBB0_801
	s_mul_hi_u32 s2, s95, 0xcccccccd
	s_lshr_b32 s3, s2, 6
	s_mulk_i32 s3, 0xffb0
	s_lshl_b32 s11, s95, 3
	s_add_i32 s3, s3, s95
	s_and_b32 s2, s2, 0xffffc0
	s_and_b32 s11, s11, 56
	s_or_b32 s2, s2, s11
	v_readlane_b32 s11, v252, 38
	s_lshl_b32 s3, s3, 5
	s_or_b32 s2, s2, s11
	s_and_b32 s3, s3, 0xffffff00
	s_lshl_b32 s2, s2, 8
	v_add_u32_e32 v148, s3, v161
	v_add_u32_e32 v138, s2, v157
	v_ashrrev_i32_e32 v149, 31, v148
	v_ashrrev_i32_e32 v139, 31, v138
	v_lshl_add_u64 v[176:177], s[68:69], 0, v[136:137]
	v_lshl_add_u64 v[136:137], s[70:71], 0, v[136:137]
	v_lshlrev_b64 v[148:149], 11, v[148:149]
	v_add3_u32 v0, 0, v168, v169
	v_add_u32_e32 v140, s2, v161
	v_add_u32_e32 v142, s2, v165
	v_add_u32_e32 v144, s2, v167
	v_lshlrev_b64 v[138:139], 11, v[138:139]
	v_lshl_add_u64 v[136:137], v[136:137], 0, v[148:149]
	v_lshl_add_u64 v[148:149], s[70:71], 0, v[134:135]
	v_lshl_add_u64 v[134:135], s[68:69], 0, v[134:135]
	v_readfirstlane_b32 s2, v0
	v_lshl_add_u64 v[134:135], v[134:135], 0, v[138:139]
	s_mov_b32 m0, s2
	v_ashrrev_i32_e32 v141, 31, v140
	global_load_lds_dwordx4 v[134:135], off
	v_add3_u32 v134, 0, v160, v169
	v_ashrrev_i32_e32 v143, 31, v142
	v_lshlrev_b64 v[140:141], 11, v[140:141]
	v_readfirstlane_b32 s2, v134
	v_add3_u32 v135, 0, v162, v169
	v_lshlrev_b64 v[142:143], 11, v[142:143]
	v_lshl_add_u64 v[202:203], s[70:71], 0, v[132:133]
	v_lshl_add_u64 v[132:133], s[68:69], 0, v[132:133]
	v_lshl_add_u64 v[140:141], v[176:177], 0, v[140:141]
	s_mov_b32 m0, s2
	v_readfirstlane_b32 s2, v135
	v_lshl_add_u64 v[132:133], v[132:133], 0, v[142:143]
	global_load_lds_dwordx4 v[140:141], off
	s_mov_b32 m0, s2
	v_ashrrev_i32_e32 v145, 31, v144
	v_add_u32_e32 v146, s3, v157
	global_load_lds_dwordx4 v[132:133], off
	v_add3_u32 v132, 0, v166, v169
	v_ashrrev_i32_e32 v147, 31, v146
	v_lshl_add_u64 v[200:201], s[68:69], 0, v[130:131]
	v_lshlrev_b64 v[144:145], 11, v[144:145]
	v_readfirstlane_b32 s2, v132
	v_add_u32_e32 v0, 0x8000, v0
	v_add_u32_e32 v150, s3, v165
	v_add_u32_e32 v152, s3, v167
	v_lshlrev_b64 v[146:147], 11, v[146:147]
	v_lshl_add_u64 v[144:145], v[200:201], 0, v[144:145]
	s_mov_b32 m0, s2
	v_readfirstlane_b32 s2, v0
	v_add_u32_e32 v0, 0x8000, v134
	v_ashrrev_i32_e32 v151, 31, v150
	v_ashrrev_i32_e32 v153, 31, v152
	v_lshl_add_u64 v[146:147], v[148:149], 0, v[146:147]
	global_load_lds_dwordx4 v[144:145], off
	s_mov_b32 m0, s2
	v_readfirstlane_b32 s2, v0
	v_add_u32_e32 v0, 0x8000, v135
	v_lshlrev_b64 v[150:151], 11, v[150:151]
	v_lshlrev_b64 v[152:153], 11, v[152:153]
	global_load_lds_dwordx4 v[146:147], off
	s_mov_b32 m0, s2
	v_readfirstlane_b32 s2, v0
	v_add_u32_e32 v0, 0x8000, v132
	v_lshl_add_u64 v[152:153], s[70:71], 0, v[152:153]
	v_lshl_add_u64 v[150:151], v[202:203], 0, v[150:151]
	global_load_lds_dwordx4 v[136:137], off
	s_mov_b32 m0, s2
	v_readfirstlane_b32 s2, v0
	global_load_lds_dwordx4 v[150:151], off
	v_lshl_add_u64 v[130:131], v[152:153], 0, v[130:131]
	s_mov_b32 m0, s2
	s_nop 0
	global_load_lds_dwordx4 v[130:131], off

; #define MFMA(a, b, c) __builtin_amdgcn_mfma_f32_32x32x16_bf16((a), (b), (c), 0, 0, 0)
;     ...
;     auto compute2 = [&](int buf) {
;       const char* lb = L0 + buf * BUFB;
; #pragma unroll
;       for (int ks = 0; ks < 4; ++ks) {
;         const int c = ks * 2 + hh;
;         bf16x8 wf[2], xf[MI];
; #pragma unroll
;         for (int j = 0; j < 2; ++j) { const int r = wn * 64 + j * 32 + l32; wf[j] = *(const bf16x8*)(lb + 256 * 128 + r * 128 + ((c ^ ((r >> 1) & 7)) << 4)); }
; #pragma unroll
;         for (int i = 0; i < MI; ++i) { const int r = wm * (MI * 32) + i * 32 + l32; xf[i] = *(const bf16x8*)(lb + r * 128 + ((c ^ ((r >> 1) & 7)) << 4)); }
; #pragma unroll
;         for (int i = 0; i < MI; ++i) {
;           acc[i][0] = MFMA(wf[0], xf[i], acc[i][0]);
;           acc[i][1] = MFMA(wf[1], xf[i], acc[i][1]);
;         }
;       }
;     ...
;       for (int kt = 0; kt < nk; ++kt) {
;         const int buf = kt & 1;
;         if (kt + 1 < nk) issue(kt + 1, buf ^ 1);
;         else if (chain & 2) issue_at(nmt * 256, nnt * BN, 0, buf ^ 1);
;         compute2(buf);
;         asm volatile("s_waitcnt vmcnt(0)" ::: "memory");
;         __syncthreads();
;       }
.LBB0_1274:
	v_writelane_b32 v255, s62, 0
	v_writelane_b32 v255, s63, 1
	v_writelane_b32 v255, s64, 2
	v_writelane_b32 v255, s65, 3
	v_writelane_b32 v255, s66, 4
	v_add_u32_e32 v228, v177, v178
	v_add_u32_e32 v229, v169, v178
	v_add_u32_e32 v230, v170, v178
	v_add_u32_e32 v231, v172, v178
	s_nop 0
	v_readfirstlane_b32 s62, v228
	v_readfirstlane_b32 s63, v229
	v_readfirstlane_b32 s64, v230
	v_readfirstlane_b32 s65, v231
	s_and_b32 s59, s56, 0x10000
	s_xor_b32 s60, s59, 0x10000
	s_add_i32 s57, s58, 1
	s_add_i32 s60, s60, 0
	s_cmp_lt_u32 s58, 21
	s_cselect_b64 vcc, -1, 0
	v_add_u32_e32 v233, s59, v201
	v_add_u32_e32 v230, v233, v175
	v_add_u32_e32 v234, v233, v174
	ds_read_b128 v[202:205], v230 offset:32768
	ds_read_b128 v[206:209], v230 offset:36864
	ds_read_b128 v[210:213], v234
	ds_read_b128 v[214:217], v234 offset:4096
	ds_read_b128 v[218:221], v234 offset:8192
	ds_read_b128 v[222:225], v234 offset:12288
	s_add_i32 s66, s60, 0x8000
	v_lshl_add_u64 v[226:227], v[160:161], 0, s[2:3]
	v_lshl_add_u64 v[228:229], v[144:145], 0, s[2:3]
	v_cndmask_b32_e32 v227, v229, v227, vcc
	v_cndmask_b32_e32 v226, v228, v226, vcc
	v_lshl_add_u64 v[226:227], v[0:1], 1, v[226:227]
	s_add_i32 m0, s60, s62
	v_lshl_add_u64 v[228:229], v[142:143], 0, s[2:3]
	global_load_lds_dwordx4 v[226:227], off
	v_lshl_add_u64 v[226:227], v[158:159], 0, s[2:3]
	v_cndmask_b32_e32 v227, v229, v227, vcc
	v_cndmask_b32_e32 v226, v228, v226, vcc
	v_lshl_add_u64 v[226:227], v[130:131], 1, v[226:227]
	s_add_i32 m0, s60, s63
	v_lshl_add_u64 v[228:229], v[140:141], 0, s[2:3]
	global_load_lds_dwordx4 v[226:227], off
	v_lshl_add_u64 v[226:227], v[156:157], 0, s[2:3]
	v_cndmask_b32_e32 v227, v229, v227, vcc
	v_cndmask_b32_e32 v226, v228, v226, vcc
	v_lshl_add_u64 v[226:227], v[132:133], 1, v[226:227]
	s_add_i32 m0, s60, s64
	v_lshl_add_u64 v[228:229], v[138:139], 0, s[2:3]
	global_load_lds_dwordx4 v[226:227], off
	v_lshl_add_u64 v[226:227], v[154:155], 0, s[2:3]
	v_cndmask_b32_e32 v226, v228, v226, vcc
	v_cndmask_b32_e32 v227, v229, v227, vcc
	s_add_i32 m0, s60, s65
	v_lshl_add_u64 v[226:227], v[134:135], 1, v[226:227]
	global_load_lds_dwordx4 v[226:227], off
	s_add_i32 m0, s66, s62
	v_lshl_add_u64 v[226:227], v[146:147], 0, s[2:3]
	global_load_lds_dwordx4 v[226:227], off
	s_add_i32 m0, s66, s63
	v_lshl_add_u64 v[226:227], v[148:149], 0, s[2:3]
	global_load_lds_dwordx4 v[226:227], off
	s_add_i32 m0, s66, s64
	v_lshl_add_u64 v[226:227], v[150:151], 0, s[2:3]
	global_load_lds_dwordx4 v[226:227], off
	v_lshl_add_u64 v[226:227], v[152:153], 0, s[2:3]
	s_add_i32 m0, s66, s65
	s_add_i32 s58, s59, 0
	global_load_lds_dwordx4 v[226:227], off
	v_add_u32_e32 v233, s59, v200
	v_add_u32_e32 v230, v233, v175
	v_add_u32_e32 v234, v233, v174
	s_waitcnt lgkmcnt(3)
	v_mfma_f32_32x32x16_bf16 v[114:129], v[202:205], v[210:213], 0
	s_add_u32 s2, s2, 0x80
	s_addc_u32 s3, s3, 0
	s_add_i32 s56, s56, 0x10000
	s_cmpk_eq_i32 s2, 0x1580
	s_mov_b32 s58, s57
	ds_read_b128 v[240:243], v230 offset:32768
	ds_read_b128 v[244:247], v230 offset:36864
	v_mfma_f32_32x32x16_bf16 v[98:113], v[206:209], v[210:213], 0
	ds_read_b128 v[248:251], v234
	s_waitcnt lgkmcnt(5)
	v_mfma_f32_32x32x16_bf16 v[82:97], v[202:205], v[214:217], 0
	v_mfma_f32_32x32x16_bf16 v[66:81], v[206:209], v[214:217], 0
	ds_read_b128 v[214:217], v234 offset:4096
	s_waitcnt lgkmcnt(5)
	v_mfma_f32_32x32x16_bf16 v[50:65], v[202:205], v[218:221], 0
	v_mfma_f32_32x32x16_bf16 v[34:49], v[206:209], v[218:221], 0
	ds_read_b128 v[218:221], v234 offset:8192
	s_waitcnt lgkmcnt(5)
	v_mfma_f32_32x32x16_bf16 v[18:33], v[202:205], v[222:225], 0
	v_mfma_f32_32x32x16_bf16 v[2:17], v[206:209], v[222:225], 0
	ds_read_b128 v[222:225], v234 offset:12288
	s_branch .Lgemm_g1_1274
.Lgemm_rot_1274:
	v_add_u32_e32 v233, s59, v200
	v_add_u32_e32 v230, v233, v175
	v_add_u32_e32 v234, v233, v174
	s_waitcnt lgkmcnt(3)
	v_mfma_f32_32x32x16_bf16 v[114:129], v[202:205], v[210:213], v[114:129]
	s_add_u32 s2, s2, 0x80
	s_addc_u32 s3, s3, 0
	s_add_i32 s56, s56, 0x10000
	s_cmpk_eq_i32 s2, 0x1580
	s_mov_b32 s58, s57
	ds_read_b128 v[240:243], v230 offset:32768
	ds_read_b128 v[244:247], v230 offset:36864
	v_mfma_f32_32x32x16_bf16 v[98:113], v[206:209], v[210:213], v[98:113]
	ds_read_b128 v[248:251], v234
	s_waitcnt lgkmcnt(5)
	v_mfma_f32_32x32x16_bf16 v[82:97], v[202:205], v[214:217], v[82:97]
	v_mfma_f32_32x32x16_bf16 v[66:81], v[206:209], v[214:217], v[66:81]
	ds_read_b128 v[214:217], v234 offset:4096
	s_waitcnt lgkmcnt(5)
	v_mfma_f32_32x32x16_bf16 v[50:65], v[202:205], v[218:221], v[50:65]
	v_mfma_f32_32x32x16_bf16 v[34:49], v[206:209], v[218:221], v[34:49]
	ds_read_b128 v[218:221], v234 offset:8192
	s_waitcnt lgkmcnt(5)
	v_mfma_f32_32x32x16_bf16 v[18:33], v[202:205], v[222:225], v[18:33]
	v_mfma_f32_32x32x16_bf16 v[2:17], v[206:209], v[222:225], v[2:17]
	ds_read_b128 v[222:225], v234 offset:12288
; #define MFMA(a, b, c) __builtin_amdgcn_mfma_f32_32x32x16_bf16((a), (b), (c), 0, 0, 0)
;     ...
;     auto compute2 = [&](int buf) {
;       const char* lb = L0 + buf * BUFB;
; #pragma unroll
;       for (int ks = 0; ks < 4; ++ks) {
;         const int c = ks * 2 + hh;
;         bf16x8 wf[2], xf[MI];
; #pragma unroll
;         for (int j = 0; j < 2; ++j) { const int r = wn * 64 + j * 32 + l32; wf[j] = *(const bf16x8*)(lb + 256 * 128 + r * 128 + ((c ^ ((r >> 1) & 7)) << 4)); }
; #pragma unroll
;         for (int i = 0; i < MI; ++i) { const int r = wm * (MI * 32) + i * 32 + l32; xf[i] = *(const bf16x8*)(lb + r * 128 + ((c ^ ((r >> 1) & 7)) << 4)); }
; #pragma unroll
;         for (int i = 0; i < MI; ++i) {
;           acc[i][0] = MFMA(wf[0], xf[i], acc[i][0]);
;           acc[i][1] = MFMA(wf[1], xf[i], acc[i][1]);
;         }
;       }
;     ...
;       for (int kt = 0; kt < nk; ++kt) {
;         const int buf = kt & 1;
;         if (kt + 1 < nk) issue(kt + 1, buf ^ 1);
;         else if (chain & 2) issue_at(nmt * 256, nnt * BN, 0, buf ^ 1);
;         compute2(buf);
;         asm volatile("s_waitcnt vmcnt(0)" ::: "memory");
;         __syncthreads();
;       }
.Lgemm_g1_1274:
	v_add_u32_e32 v233, s59, v199
	v_add_u32_e32 v230, v233, v175
	v_add_u32_e32 v234, v233, v174
	s_waitcnt lgkmcnt(3)
	v_mfma_f32_32x32x16_bf16 v[114:129], v[240:243], v[248:251], v[114:129]
	ds_read_b128 v[202:205], v230 offset:32768
	ds_read_b128 v[206:209], v230 offset:36864
	v_mfma_f32_32x32x16_bf16 v[98:113], v[244:247], v[248:251], v[98:113]
	ds_read_b128 v[210:213], v234
	s_waitcnt lgkmcnt(5)
	v_mfma_f32_32x32x16_bf16 v[82:97], v[240:243], v[214:217], v[82:97]
	v_mfma_f32_32x32x16_bf16 v[66:81], v[244:247], v[214:217], v[66:81]
	ds_read_b128 v[214:217], v234 offset:4096
	s_waitcnt lgkmcnt(5)
	v_mfma_f32_32x32x16_bf16 v[50:65], v[240:243], v[218:221], v[50:65]
	v_mfma_f32_32x32x16_bf16 v[34:49], v[244:247], v[218:221], v[34:49]
	ds_read_b128 v[218:221], v234 offset:8192
	s_waitcnt lgkmcnt(5)
	v_mfma_f32_32x32x16_bf16 v[18:33], v[240:243], v[222:225], v[18:33]
	v_mfma_f32_32x32x16_bf16 v[2:17], v[244:247], v[222:225], v[2:17]
	ds_read_b128 v[222:225], v234 offset:12288
	v_add_u32_e32 v233, s59, v176
	v_add_u32_e32 v230, v233, v175
	v_add_u32_e32 v234, v233, v174
	s_waitcnt lgkmcnt(3)
	v_mfma_f32_32x32x16_bf16 v[114:129], v[202:205], v[210:213], v[114:129]
	ds_read_b128 v[240:243], v230 offset:32768
	ds_read_b128 v[244:247], v230 offset:36864
	v_mfma_f32_32x32x16_bf16 v[98:113], v[206:209], v[210:213], v[98:113]
	ds_read_b128 v[248:251], v234
	s_waitcnt lgkmcnt(5)
	v_mfma_f32_32x32x16_bf16 v[82:97], v[202:205], v[214:217], v[82:97]
	v_mfma_f32_32x32x16_bf16 v[66:81], v[206:209], v[214:217], v[66:81]
	ds_read_b128 v[214:217], v234 offset:4096
	s_waitcnt lgkmcnt(5)
	v_mfma_f32_32x32x16_bf16 v[50:65], v[202:205], v[218:221], v[50:65]
	v_mfma_f32_32x32x16_bf16 v[34:49], v[206:209], v[218:221], v[34:49]
	ds_read_b128 v[218:221], v234 offset:8192
	s_waitcnt lgkmcnt(5)
	v_mfma_f32_32x32x16_bf16 v[18:33], v[202:205], v[222:225], v[18:33]
	v_mfma_f32_32x32x16_bf16 v[2:17], v[206:209], v[222:225], v[2:17]
	ds_read_b128 v[222:225], v234 offset:12288
	s_waitcnt vmcnt(0)
	s_waitcnt vmcnt(0) lgkmcnt(0)
	s_cbranch_scc1 .Lgemm_exit_1274
	s_and_b32 s59, s56, 0x10000
	s_xor_b32 s60, s59, 0x10000
	s_add_i32 s57, s58, 1
	s_add_i32 s60, s60, 0
	s_cmp_lt_u32 s58, 21
	s_cselect_b64 vcc, -1, 0
	v_add_u32_e32 v233, s59, v201
	v_add_u32_e32 v230, v233, v175
	v_add_u32_e32 v234, v233, v174
	s_barrier
	ds_read_b128 v[202:205], v230 offset:32768
	ds_read_b128 v[206:209], v230 offset:36864
	ds_read_b128 v[210:213], v234
	v_mfma_f32_32x32x16_bf16 v[114:129], v[240:243], v[248:251], v[114:129]
	s_add_i32 s66, s60, 0x8000
	v_lshl_add_u64 v[226:227], v[160:161], 0, s[2:3]
	v_lshl_add_u64 v[228:229], v[144:145], 0, s[2:3]
	v_cndmask_b32_e32 v227, v229, v227, vcc
	v_cndmask_b32_e32 v226, v228, v226, vcc
	v_lshl_add_u64 v[226:227], v[0:1], 1, v[226:227]
	v_mfma_f32_32x32x16_bf16 v[98:113], v[244:247], v[248:251], v[98:113]
	s_add_i32 m0, s60, s62
	v_lshl_add_u64 v[228:229], v[142:143], 0, s[2:3]
	global_load_lds_dwordx4 v[226:227], off
	v_lshl_add_u64 v[226:227], v[158:159], 0, s[2:3]
	v_cndmask_b32_e32 v227, v229, v227, vcc
	v_cndmask_b32_e32 v226, v228, v226, vcc
	v_mfma_f32_32x32x16_bf16 v[82:97], v[240:243], v[214:217], v[82:97]
	v_lshl_add_u64 v[226:227], v[130:131], 1, v[226:227]
	s_add_i32 m0, s60, s63
	v_lshl_add_u64 v[228:229], v[140:141], 0, s[2:3]
	global_load_lds_dwordx4 v[226:227], off
	v_lshl_add_u64 v[226:227], v[156:157], 0, s[2:3]
	v_cndmask_b32_e32 v227, v229, v227, vcc
	v_mfma_f32_32x32x16_bf16 v[66:81], v[244:247], v[214:217], v[66:81]
	ds_read_b128 v[214:217], v234 offset:4096
	v_cndmask_b32_e32 v226, v228, v226, vcc
	v_lshl_add_u64 v[226:227], v[132:133], 1, v[226:227]
	s_add_i32 m0, s60, s64
	v_lshl_add_u64 v[228:229], v[138:139], 0, s[2:3]
	global_load_lds_dwordx4 v[226:227], off
	v_lshl_add_u64 v[226:227], v[154:155], 0, s[2:3]
	v_mfma_f32_32x32x16_bf16 v[50:65], v[240:243], v[218:221], v[50:65]
	v_cndmask_b32_e32 v226, v228, v226, vcc
	v_cndmask_b32_e32 v227, v229, v227, vcc
	s_add_i32 m0, s60, s65
	v_lshl_add_u64 v[226:227], v[134:135], 1, v[226:227]
	global_load_lds_dwordx4 v[226:227], off
	s_add_i32 m0, s66, s62
	v_mfma_f32_32x32x16_bf16 v[34:49], v[244:247], v[218:221], v[34:49]
	ds_read_b128 v[218:221], v234 offset:8192
	v_lshl_add_u64 v[226:227], v[146:147], 0, s[2:3]
	global_load_lds_dwordx4 v[226:227], off
	s_add_i32 m0, s66, s63
	v_lshl_add_u64 v[226:227], v[148:149], 0, s[2:3]
	global_load_lds_dwordx4 v[226:227], off
	s_add_i32 m0, s66, s64
	v_mfma_f32_32x32x16_bf16 v[18:33], v[240:243], v[222:225], v[18:33]
	v_lshl_add_u64 v[226:227], v[150:151], 0, s[2:3]
	global_load_lds_dwordx4 v[226:227], off
	v_lshl_add_u64 v[226:227], v[152:153], 0, s[2:3]
	s_add_i32 m0, s66, s65
	s_add_i32 s58, s59, 0
	global_load_lds_dwordx4 v[226:227], off
	v_mfma_f32_32x32x16_bf16 v[2:17], v[244:247], v[222:225], v[2:17]
	ds_read_b128 v[222:225], v234 offset:12288
	s_branch .Lgemm_rot_1274
;     ...
;       for (int kt = 0; kt < nk; ++kt) {
;         const int buf = kt & 1;
;         if (kt + 1 < nk) issue(kt + 1, buf ^ 1);
;         else if (chain & 2) issue_at(nmt * 256, nnt * BN, 0, buf ^ 1);
;         compute2(buf);
;         asm volatile("s_waitcnt vmcnt(0)" ::: "memory");
;         __syncthreads();
;       }
; template <int MODE, int EPI, int BN>
; DI void gemm_phase(CP p, const GArgs& g, int NT, char* smem) {
;     ...
;   for (int e = j; e < total; e += nj) {
;     const int grp = e / (8 * NT);
;     const int rem = e - grp * 8 * NT;
;     const int e2 = e + nj;
;     const bool has_next = can_chain && e2 < total;
;     const int grp2 = e2 / (8 * NT), rem2 = e2 - grp2 * 8 * NT;
;     const int chain = can_chain ? ((first ? 0 : 1) | (has_next ? 2 : 0)) : 0;
;     gemm_tile<MODE, EPI, BN>(p, g, x + 8 * (grp * 8 + (rem & 7)), rem >> 3, smem, chain, x + 8 * (grp2 * 8 + (rem2 & 7)), rem2 >> 3);
.Lgemm_exit_1274:
	s_barrier
	v_readlane_b32 s62, v255, 0
	v_readlane_b32 s63, v255, 1
	v_readlane_b32 s64, v255, 2
	v_readlane_b32 s65, v255, 3
	v_readlane_b32 s66, v255, 4
	v_mfma_f32_32x32x16_bf16 v[114:129], v[240:243], v[248:251], v[114:129]
	v_mfma_f32_32x32x16_bf16 v[98:113], v[244:247], v[248:251], v[98:113]
	v_mfma_f32_32x32x16_bf16 v[82:97], v[240:243], v[214:217], v[82:97]
	v_mfma_f32_32x32x16_bf16 v[66:81], v[244:247], v[214:217], v[66:81]
	v_mfma_f32_32x32x16_bf16 v[50:65], v[240:243], v[218:221], v[50:65]
	v_mfma_f32_32x32x16_bf16 v[34:49], v[244:247], v[218:221], v[34:49]
	v_mfma_f32_32x32x16_bf16 v[18:33], v[240:243], v[222:225], v[18:33]
	v_mfma_f32_32x32x16_bf16 v[2:17], v[244:247], v[222:225], v[2:17]
	s_add_i32 s15, s15, s10
	s_cmp_gt_u32 s15, 63
	s_cselect_b64 s[58:59], -1, 0
	s_and_b64 vcc, exec, s[58:59]
	s_cbranch_vccnz .LBB0_1277
	s_lshr_b32 s2, s15, 2
	s_and_b32 s2, s2, 0xffffff8
	s_and_b32 s3, s15, 7
	s_or_b32 s3, s2, s3
	s_lshl_b32 s2, s2, 7
	s_lshl_b32 s56, s15, 5
	s_sub_i32 s2, s56, s2
	s_lshl_b32 s3, s3, 11
	s_and_b32 s2, s2, 0xffffff00
	s_or_b32 s3, s3, s71
	v_add_u32_e32 v144, s2, v173
	v_lshlrev_b64 v[130:131], 1, v[130:131]
	v_mov_b64_e32 v[142:143], s[46:47]
	v_lshlrev_b64 v[132:133], 1, v[132:133]
	v_add_u32_e32 v0, s3, v163
	v_add_u32_e32 v148, s3, v168
	v_add_u32_e32 v149, s3, v171
	v_add_u32_e32 v150, s3, v173
	v_add_u32_e32 v151, s2, v163
	v_add_u32_e32 v146, s2, v168
	v_add_u32_e32 v147, s2, v171
	v_lshl_add_u64 v[138:139], s[42:43], 0, v[130:131]
	v_lshlrev_b64 v[134:135], 1, v[134:135]
	v_lshl_add_u64 v[130:131], s[46:47], 0, v[130:131]
	v_mad_i64_i32 v[142:143], s[2:3], v144, s96, v[142:143]
	v_lshl_add_u64 v[144:145], s[46:47], 0, v[132:133]
	v_lshl_add_u64 v[140:141], s[42:43], 0, v[134:135]
	v_mad_i64_i32 v[144:145], s[2:3], v147, s96, v[144:145]
	v_mad_i64_i32 v[130:131], s[2:3], v146, s96, v[130:131]
	v_lshl_add_u64 v[146:147], s[46:47], 0, v[136:137]
	v_lshl_add_u64 v[132:133], s[42:43], 0, v[132:133]
	v_lshl_add_u64 v[136:137], s[42:43], 0, v[136:137]
	v_mad_i64_i32 v[146:147], s[2:3], v151, s96, v[146:147]
	v_mad_i64_i32 v[140:141], s[2:3], v150, s29, v[140:141]
	v_mad_i64_i32 v[132:133], s[2:3], v149, s29, v[132:133]
	v_mad_i64_i32 v[138:139], s[2:3], v148, s29, v[138:139]
	v_mad_i64_i32 v[136:137], s[2:3], v0, s29, v[136:137]
	v_add3_u32 v0, 0, v177, v178
	s_nop 0
	v_readfirstlane_b32 s2, v0
	s_mov_b32 m0, s2
	v_add_u32_e32 v0, 0x8000, v0
	global_load_lds_dwordx4 v[136:137], off
	v_add3_u32 v136, 0, v169, v178
	v_add3_u32 v137, 0, v170, v178
	v_readfirstlane_b32 s2, v136
	s_mov_b32 m0, s2
	v_readfirstlane_b32 s2, v137
	global_load_lds_dwordx4 v[138:139], off
	s_mov_b32 m0, s2
	s_nop 0
	global_load_lds_dwordx4 v[132:133], off
	v_add3_u32 v132, 0, v172, v178
	s_nop 0
	v_readfirstlane_b32 s2, v132
	s_mov_b32 m0, s2
	v_readfirstlane_b32 s2, v0
	v_add_u32_e32 v0, 0x8000, v136
	global_load_lds_dwordx4 v[140:141], off
	s_mov_b32 m0, s2
	v_readfirstlane_b32 s2, v0
	v_add_u32_e32 v0, 0x8000, v137
	global_load_lds_dwordx4 v[146:147], off
	s_mov_b32 m0, s2
	v_readfirstlane_b32 s2, v0
	v_add_u32_e32 v0, 0x8000, v132
	global_load_lds_dwordx4 v[130:131], off
	s_mov_b32 m0, s2
	v_readfirstlane_b32 s2, v0
	global_load_lds_dwordx4 v[144:145], off
	v_lshl_add_u64 v[130:131], v[142:143], 0, v[134:135]
	s_mov_b32 m0, s2
	s_nop 0
	global_load_lds_dwordx4 v[130:131], off

; #define MFMA(a, b, c) __builtin_amdgcn_mfma_f32_32x32x16_bf16((a), (b), (c), 0, 0, 0)
;     ...
;     auto compute2 = [&](int buf) {
;       const char* lb = L0 + buf * BUFB;
; #pragma unroll
;       for (int ks = 0; ks < 4; ++ks) {
;         const int c = ks * 2 + hh;
;         bf16x8 wf[2], xf[MI];
; #pragma unroll
;         for (int j = 0; j < 2; ++j) { const int r = wn * 64 + j * 32 + l32; wf[j] = *(const bf16x8*)(lb + 256 * 128 + r * 128 + ((c ^ ((r >> 1) & 7)) << 4)); }
; #pragma unroll
;         for (int i = 0; i < MI; ++i) { const int r = wm * (MI * 32) + i * 32 + l32; xf[i] = *(const bf16x8*)(lb + r * 128 + ((c ^ ((r >> 1) & 7)) << 4)); }
; #pragma unroll
;         for (int i = 0; i < MI; ++i) {
;           acc[i][0] = MFMA(wf[0], xf[i], acc[i][0]);
;           acc[i][1] = MFMA(wf[1], xf[i], acc[i][1]);
;         }
;       }
;     ...
;       for (int kt = 0; kt < nk; ++kt) {
;         const int buf = kt & 1;
;         if (kt + 1 < nk) issue(kt + 1, buf ^ 1);
;         else if (chain & 2) issue_at(nmt * 256, nnt * BN, 0, buf ^ 1);
;         compute2(buf);
;         asm volatile("s_waitcnt vmcnt(0)" ::: "memory");
;         __syncthreads();
;       }
.LBB0_1371:
	s_waitcnt vmcnt(16)
	s_barrier
	v_writelane_b32 v255, s60, 0
	v_writelane_b32 v255, s61, 1
	v_writelane_b32 v255, s62, 2
	v_writelane_b32 v255, s63, 3
	v_writelane_b32 v255, s64, 4
	v_add_u32_e32 v0, v167, v168
	v_add_u32_e32 v175, v157, v168
	v_add_u32_e32 v178, v159, v168
	v_add_u32_e32 v199, v165, v168
	s_nop 0
	v_readfirstlane_b32 s60, v0
	v_readfirstlane_b32 s61, v175
	v_readfirstlane_b32 s62, v178
	v_readfirstlane_b32 s63, v199
	s_and_b32 s17, s16, 0x10000
	s_xor_b32 s43, s17, 0x10000
	s_add_i32 s43, s43, 0
	s_add_i32 s17, s17, 0
	v_add_u32_e32 v0, s17, v174
	v_add_u32_e32 v175, v0, v170
	v_add_u32_e32 v0, v0, v169
	ds_read_b128 v[200:203], v175 offset:32768
	ds_read_b128 v[204:207], v175 offset:36864
	ds_read_b128 v[208:211], v0
	ds_read_b128 v[212:215], v0 offset:4096
	ds_read_b128 v[216:219], v0 offset:8192
	ds_read_b128 v[220:223], v0 offset:12288
	s_add_i32 s64, s43, 0x8000
	s_add_i32 m0, s43, s60
	v_lshl_add_u64 v[176:177], v[152:153], 0, s[10:11]
	global_load_lds_dwordx4 v[176:177], off
	s_add_i32 m0, s43, s61
	v_lshl_add_u64 v[176:177], v[150:151], 0, s[10:11]
	global_load_lds_dwordx4 v[176:177], off
	s_add_i32 m0, s43, s62
	v_lshl_add_u64 v[176:177], v[148:149], 0, s[10:11]
	global_load_lds_dwordx4 v[176:177], off
	s_add_i32 m0, s43, s63
	v_lshl_add_u64 v[176:177], v[146:147], 0, s[10:11]
	global_load_lds_dwordx4 v[176:177], off
	s_add_i32 m0, s64, s60
	v_lshl_add_u64 v[176:177], v[144:145], 0, s[10:11]
	global_load_lds_dwordx4 v[176:177], off
	s_add_i32 m0, s64, s61
	v_lshl_add_u64 v[176:177], v[142:143], 0, s[10:11]
	global_load_lds_dwordx4 v[176:177], off
	s_add_i32 m0, s64, s62
	v_lshl_add_u64 v[176:177], v[140:141], 0, s[10:11]
	global_load_lds_dwordx4 v[176:177], off
	s_add_i32 m0, s64, s63
	v_lshl_add_u64 v[176:177], v[138:139], 0, s[10:11]
	global_load_lds_dwordx4 v[176:177], off
	v_add_u32_e32 v0, s17, v173
	v_add_u32_e32 v175, v0, v170
	v_add_u32_e32 v0, v0, v169
	s_waitcnt lgkmcnt(3)
	v_mfma_f32_32x32x16_bf16 v[114:129], v[200:203], v[208:211], 0
	s_add_i32 s16, s16, 0x10000
	s_add_u32 s10, s10, 0x80
	s_addc_u32 s11, s11, 0
	s_cmpk_eq_i32 s10, 0x780
	ds_read_b128 v[224:227], v175 offset:32768
	ds_read_b128 v[228:231], v175 offset:36864
	v_mfma_f32_32x32x16_bf16 v[98:113], v[204:207], v[208:211], 0
	ds_read_b128 v[232:235], v0
	ds_read_b128 v[240:243], v0 offset:4096
	s_waitcnt lgkmcnt(6)
	v_mfma_f32_32x32x16_bf16 v[82:97], v[200:203], v[212:215], 0
	ds_read_b128 v[244:247], v0 offset:8192
	ds_read_b128 v[248:251], v0 offset:12288
	v_mfma_f32_32x32x16_bf16 v[66:81], v[204:207], v[212:215], 0
	s_waitcnt lgkmcnt(7)
	v_mfma_f32_32x32x16_bf16 v[50:65], v[200:203], v[216:219], 0
	v_mfma_f32_32x32x16_bf16 v[34:49], v[204:207], v[216:219], 0
	s_waitcnt lgkmcnt(6)
	v_mfma_f32_32x32x16_bf16 v[18:33], v[200:203], v[220:223], 0
	v_mfma_f32_32x32x16_bf16 v[2:17], v[204:207], v[220:223], 0
	s_branch .Lgemm_g1_1371
.Lgemm_rot_1371:
	v_add_u32_e32 v0, s17, v173
	v_add_u32_e32 v175, v0, v170
	v_add_u32_e32 v0, v0, v169
	s_waitcnt lgkmcnt(3)
	v_mfma_f32_32x32x16_bf16 v[114:129], v[200:203], v[208:211], v[114:129]
	s_add_i32 s16, s16, 0x10000
	s_add_u32 s10, s10, 0x80
	s_addc_u32 s11, s11, 0
	s_cmpk_eq_i32 s10, 0x780
	ds_read_b128 v[224:227], v175 offset:32768
	ds_read_b128 v[228:231], v175 offset:36864
	v_mfma_f32_32x32x16_bf16 v[98:113], v[204:207], v[208:211], v[98:113]
	ds_read_b128 v[232:235], v0
	ds_read_b128 v[240:243], v0 offset:4096
	s_waitcnt lgkmcnt(6)
	v_mfma_f32_32x32x16_bf16 v[82:97], v[200:203], v[212:215], v[82:97]
	ds_read_b128 v[244:247], v0 offset:8192
	ds_read_b128 v[248:251], v0 offset:12288
	v_mfma_f32_32x32x16_bf16 v[66:81], v[204:207], v[212:215], v[66:81]
	s_waitcnt lgkmcnt(7)
	v_mfma_f32_32x32x16_bf16 v[50:65], v[200:203], v[216:219], v[50:65]
	v_mfma_f32_32x32x16_bf16 v[34:49], v[204:207], v[216:219], v[34:49]
	s_waitcnt lgkmcnt(6)
	v_mfma_f32_32x32x16_bf16 v[18:33], v[200:203], v[220:223], v[18:33]
	v_mfma_f32_32x32x16_bf16 v[2:17], v[204:207], v[220:223], v[2:17]
.Lgemm_g1_1371:
	v_add_u32_e32 v0, s17, v172
	v_add_u32_e32 v175, v0, v170
	v_add_u32_e32 v0, v0, v169
	s_waitcnt lgkmcnt(3)
	v_mfma_f32_32x32x16_bf16 v[114:129], v[224:227], v[232:235], v[114:129]
	ds_read_b128 v[200:203], v175 offset:32768
	ds_read_b128 v[204:207], v175 offset:36864
	v_mfma_f32_32x32x16_bf16 v[98:113], v[228:231], v[232:235], v[98:113]
	ds_read_b128 v[208:211], v0
	ds_read_b128 v[212:215], v0 offset:4096
	s_waitcnt lgkmcnt(6)
	v_mfma_f32_32x32x16_bf16 v[82:97], v[224:227], v[240:243], v[82:97]
	ds_read_b128 v[216:219], v0 offset:8192
	ds_read_b128 v[220:223], v0 offset:12288
	v_mfma_f32_32x32x16_bf16 v[66:81], v[228:231], v[240:243], v[66:81]
	s_waitcnt lgkmcnt(7)
	v_mfma_f32_32x32x16_bf16 v[50:65], v[224:227], v[244:247], v[50:65]
	v_mfma_f32_32x32x16_bf16 v[34:49], v[228:231], v[244:247], v[34:49]
	s_waitcnt lgkmcnt(6)
	v_mfma_f32_32x32x16_bf16 v[18:33], v[224:227], v[248:251], v[18:33]
	v_mfma_f32_32x32x16_bf16 v[2:17], v[228:231], v[248:251], v[2:17]
	v_add_u32_e32 v0, s17, v171
	v_add_u32_e32 v175, v0, v170
	v_add_u32_e32 v0, v0, v169
	s_waitcnt lgkmcnt(3)
	v_mfma_f32_32x32x16_bf16 v[114:129], v[200:203], v[208:211], v[114:129]
	ds_read_b128 v[224:227], v175 offset:32768
	ds_read_b128 v[228:231], v175 offset:36864
	v_mfma_f32_32x32x16_bf16 v[98:113], v[204:207], v[208:211], v[98:113]
	ds_read_b128 v[232:235], v0
	ds_read_b128 v[240:243], v0 offset:4096
	s_waitcnt lgkmcnt(6)
	v_mfma_f32_32x32x16_bf16 v[82:97], v[200:203], v[212:215], v[82:97]
	ds_read_b128 v[244:247], v0 offset:8192
	ds_read_b128 v[248:251], v0 offset:12288
	v_mfma_f32_32x32x16_bf16 v[66:81], v[204:207], v[212:215], v[66:81]
	s_waitcnt lgkmcnt(7)
	v_mfma_f32_32x32x16_bf16 v[50:65], v[200:203], v[216:219], v[50:65]
	v_mfma_f32_32x32x16_bf16 v[34:49], v[204:207], v[216:219], v[34:49]
	s_waitcnt lgkmcnt(6)
	v_mfma_f32_32x32x16_bf16 v[18:33], v[200:203], v[220:223], v[18:33]
	v_mfma_f32_32x32x16_bf16 v[2:17], v[204:207], v[220:223], v[2:17]
	s_waitcnt vmcnt(0)
	s_waitcnt vmcnt(0) lgkmcnt(0)
	s_cbranch_scc1 .Lgemm_exit_1371
;     ...
;       for (int kt = 0; kt < nk; ++kt) {
;         const int buf = kt & 1;
;         if (kt + 1 < nk) issue(kt + 1, buf ^ 1);
;         else if (chain & 2) issue_at(nmt * 256, nnt * BN, 0, buf ^ 1);
;         compute2(buf);
;         asm volatile("s_waitcnt vmcnt(0)" ::: "memory");
;         __syncthreads();
;       }
; template <int MODE, int EPI, int BN>
; DI void gemm_phase(CP p, const GArgs& g, int NT, char* smem) {
;     ...
;   for (int e = j; e < total; e += nj) {
;     const int grp = e / (8 * NT);
;     const int rem = e - grp * 8 * NT;
;     const int e2 = e + nj;
;     const bool has_next = can_chain && e2 < total;
;     const int grp2 = e2 / (8 * NT), rem2 = e2 - grp2 * 8 * NT;
;     const int chain = can_chain ? ((first ? 0 : 1) | (has_next ? 2 : 0)) : 0;
;     gemm_tile<MODE, EPI, BN>(p, g, x + 8 * (grp * 8 + (rem & 7)), rem >> 3, smem, chain, x + 8 * (grp2 * 8 + (rem2 & 7)), rem2 >> 3);
	s_and_b32 s17, s16, 0x10000
	s_xor_b32 s43, s17, 0x10000
	s_add_i32 s43, s43, 0
	s_add_i32 s17, s17, 0
	v_add_u32_e32 v0, s17, v174
	v_add_u32_e32 v175, v0, v170
	v_add_u32_e32 v0, v0, v169
	s_barrier
	ds_read_b128 v[200:203], v175 offset:32768
	ds_read_b128 v[204:207], v175 offset:36864
	ds_read_b128 v[208:211], v0
	ds_read_b128 v[212:215], v0 offset:4096
	ds_read_b128 v[216:219], v0 offset:8192
	ds_read_b128 v[220:223], v0 offset:12288
	v_mfma_f32_32x32x16_bf16 v[114:129], v[224:227], v[232:235], v[114:129]
	s_add_i32 s64, s43, 0x8000
	s_add_i32 m0, s43, s60
	v_lshl_add_u64 v[176:177], v[152:153], 0, s[10:11]
	global_load_lds_dwordx4 v[176:177], off
	v_mfma_f32_32x32x16_bf16 v[98:113], v[228:231], v[232:235], v[98:113]
	s_add_i32 m0, s43, s61
	v_lshl_add_u64 v[176:177], v[150:151], 0, s[10:11]
	global_load_lds_dwordx4 v[176:177], off
	s_add_i32 m0, s43, s62
	v_mfma_f32_32x32x16_bf16 v[82:97], v[224:227], v[240:243], v[82:97]
	v_lshl_add_u64 v[176:177], v[148:149], 0, s[10:11]
	global_load_lds_dwordx4 v[176:177], off
	s_add_i32 m0, s43, s63
	v_lshl_add_u64 v[176:177], v[146:147], 0, s[10:11]
	v_mfma_f32_32x32x16_bf16 v[66:81], v[228:231], v[240:243], v[66:81]
	global_load_lds_dwordx4 v[176:177], off
	s_add_i32 m0, s64, s60
	v_lshl_add_u64 v[176:177], v[144:145], 0, s[10:11]
	global_load_lds_dwordx4 v[176:177], off
	v_mfma_f32_32x32x16_bf16 v[50:65], v[224:227], v[244:247], v[50:65]
	s_add_i32 m0, s64, s61
	v_lshl_add_u64 v[176:177], v[142:143], 0, s[10:11]
	global_load_lds_dwordx4 v[176:177], off
	s_add_i32 m0, s64, s62
	v_mfma_f32_32x32x16_bf16 v[34:49], v[228:231], v[244:247], v[34:49]
	v_lshl_add_u64 v[176:177], v[140:141], 0, s[10:11]
	global_load_lds_dwordx4 v[176:177], off
	s_add_i32 m0, s64, s63
	v_lshl_add_u64 v[176:177], v[138:139], 0, s[10:11]
	v_mfma_f32_32x32x16_bf16 v[18:33], v[224:227], v[248:251], v[18:33]
	global_load_lds_dwordx4 v[176:177], off
	v_mfma_f32_32x32x16_bf16 v[2:17], v[228:231], v[248:251], v[2:17]
	s_branch .Lgemm_rot_1371
.Lgemm_exit_1371:
	s_barrier
	v_readlane_b32 s60, v255, 0
	v_readlane_b32 s61, v255, 1
	v_readlane_b32 s62, v255, 2
	v_readlane_b32 s63, v255, 3
	v_readlane_b32 s64, v255, 4
	v_mfma_f32_32x32x16_bf16 v[114:129], v[224:227], v[232:235], v[114:129]
	v_mfma_f32_32x32x16_bf16 v[98:113], v[228:231], v[232:235], v[98:113]
	v_mfma_f32_32x32x16_bf16 v[82:97], v[224:227], v[240:243], v[82:97]
	v_mfma_f32_32x32x16_bf16 v[66:81], v[228:231], v[240:243], v[66:81]
	v_mfma_f32_32x32x16_bf16 v[50:65], v[224:227], v[244:247], v[50:65]
	v_mfma_f32_32x32x16_bf16 v[34:49], v[228:231], v[244:247], v[34:49]
	v_mfma_f32_32x32x16_bf16 v[18:33], v[224:227], v[248:251], v[18:33]
	v_mfma_f32_32x32x16_bf16 v[2:17], v[228:231], v[248:251], v[2:17]
	s_add_i32 s51, s51, s50
	s_cmpk_gt_u32 s51, 0x15f
	s_cselect_b64 s[10:11], -1, 0
	s_and_b64 vcc, exec, s[10:11]
	s_cbranch_vccnz .LBB0_1374
	s_mul_hi_u32 s16, s51, 0xba2e8ba3
	s_lshr_b32 s16, s16, 7
	s_mul_i32 s17, s16, 0xffffff50
	s_lshl_b32 s43, s51, 3
	s_add_i32 s17, s17, s51
	s_lshl_b32 s16, s16, 6
	s_and_b32 s43, s43, 56
	s_or_b32 s16, s16, s43
	s_lshl_b32 s17, s17, 5
	s_or_b32 s16, s16, s72
	s_and_b32 s17, s17, 0xffffff00
	s_lshl_b32 s16, s16, 8
	v_add_u32_e32 v148, s17, v158
	v_add_u32_e32 v138, s16, v156
	v_ashrrev_i32_e32 v149, 31, v148
	v_ashrrev_i32_e32 v139, 31, v138
	v_lshl_add_u64 v[176:177], s[46:47], 0, v[136:137]
	v_lshl_add_u64 v[136:137], s[48:49], 0, v[136:137]
	v_lshlrev_b64 v[148:149], 11, v[148:149]
	v_add3_u32 v0, 0, v167, v168
	v_add_u32_e32 v140, s16, v158
	v_add_u32_e32 v142, s16, v164
	v_add_u32_e32 v144, s16, v166
	v_lshlrev_b64 v[138:139], 11, v[138:139]
	v_lshl_add_u64 v[136:137], v[136:137], 0, v[148:149]
	v_lshl_add_u64 v[148:149], s[48:49], 0, v[134:135]
	v_lshl_add_u64 v[134:135], s[46:47], 0, v[134:135]
	v_readfirstlane_b32 s16, v0
	v_lshl_add_u64 v[134:135], v[134:135], 0, v[138:139]
	s_mov_b32 m0, s16
	v_ashrrev_i32_e32 v141, 31, v140
	global_load_lds_dwordx4 v[134:135], off
	v_add3_u32 v134, 0, v157, v168
	v_ashrrev_i32_e32 v143, 31, v142
	v_lshlrev_b64 v[140:141], 11, v[140:141]
	v_readfirstlane_b32 s16, v134
	v_add3_u32 v135, 0, v159, v168
	v_lshlrev_b64 v[142:143], 11, v[142:143]
	v_lshl_add_u64 v[202:203], s[48:49], 0, v[132:133]
	v_lshl_add_u64 v[132:133], s[46:47], 0, v[132:133]
	v_lshl_add_u64 v[140:141], v[176:177], 0, v[140:141]
	s_mov_b32 m0, s16
	v_readfirstlane_b32 s16, v135
	v_lshl_add_u64 v[132:133], v[132:133], 0, v[142:143]
	global_load_lds_dwordx4 v[140:141], off
	s_mov_b32 m0, s16
	v_ashrrev_i32_e32 v145, 31, v144
	v_add_u32_e32 v146, s17, v156
	global_load_lds_dwordx4 v[132:133], off
	v_add3_u32 v132, 0, v165, v168
	v_ashrrev_i32_e32 v147, 31, v146
	v_lshl_add_u64 v[200:201], s[46:47], 0, v[130:131]
	v_lshlrev_b64 v[144:145], 11, v[144:145]
	v_readfirstlane_b32 s16, v132
	v_add_u32_e32 v0, 0x8000, v0
	v_add_u32_e32 v150, s17, v164
	v_add_u32_e32 v152, s17, v166
	v_lshlrev_b64 v[146:147], 11, v[146:147]
	v_lshl_add_u64 v[144:145], v[200:201], 0, v[144:145]
	s_mov_b32 m0, s16
	v_readfirstlane_b32 s16, v0
	v_add_u32_e32 v0, 0x8000, v134
	v_ashrrev_i32_e32 v151, 31, v150
	v_ashrrev_i32_e32 v153, 31, v152
	v_lshl_add_u64 v[146:147], v[148:149], 0, v[146:147]
	global_load_lds_dwordx4 v[144:145], off
	s_mov_b32 m0, s16
	v_readfirstlane_b32 s16, v0
	v_add_u32_e32 v0, 0x8000, v135
	v_lshlrev_b64 v[150:151], 11, v[150:151]
	v_lshlrev_b64 v[152:153], 11, v[152:153]
	global_load_lds_dwordx4 v[146:147], off
	s_mov_b32 m0, s16
	v_readfirstlane_b32 s16, v0
	v_add_u32_e32 v0, 0x8000, v132
	v_lshl_add_u64 v[152:153], s[48:49], 0, v[152:153]
	v_lshl_add_u64 v[150:151], v[202:203], 0, v[150:151]
	global_load_lds_dwordx4 v[136:137], off
	s_mov_b32 m0, s16
	v_readfirstlane_b32 s16, v0
	global_load_lds_dwordx4 v[150:151], off
	v_lshl_add_u64 v[130:131], v[152:153], 0, v[130:131]
	s_mov_b32 m0, s16
	s_nop 0
	global_load_lds_dwordx4 v[130:131], off
